# v72 scan config plus de-serialised out-proj epilogue loads (12 in flight), batched barrier census loads, two-task-in-flight split-K reduce
# speedup vs baseline: 1.0187x; 1.0032x over previous
.LBB0_252:
	v_readlane_b32 s22, v253, 63
	v_readlane_b32 s23, v254, 0
	s_cmp_lt_i32 s22, 0
	s_mov_b64 s[22:23], -1
	v_readlane_b32 s60, v254, 50
	s_cbranch_scc0 .LBB0_270
	v_and_b32_e32 v148, 64, v208
	v_xor_b32_e32 v147, 16, v208
	v_add_u32_e32 v148, 64, v148
	v_cmp_lt_i32_e32 vcc, v147, v148
	v_lshl_add_u32 v146, s45, 8, v3
	v_readlane_b32 s28, v254, 55
	v_cndmask_b32_e32 v147, v208, v147, vcc
	v_lshlrev_b32_e32 v154, 2, v147
	v_xor_b32_e32 v147, 32, v208
	v_cmp_lt_i32_e32 vcc, v147, v148
	v_lshl_or_b32 v144, s51, 8, v151
	v_readlane_b32 s29, v254, 56
	v_cndmask_b32_e32 v147, v208, v147, vcc
	v_lshlrev_b32_e32 v153, 2, v147
	v_ashrrev_i32_e32 v147, 31, v146
	v_lshlrev_b64 v[148:149], 13, v[146:147]
	v_readlane_b32 s26, v254, 48
	v_ashrrev_i32_e32 v145, 31, v144
	v_lshl_add_u64 v[148:149], s[28:29], 0, v[148:149]
	v_lshlrev_b64 v[156:157], 12, v[146:147]
	v_readlane_b32 s27, v254, 49
	v_lshl_add_u64 v[148:149], v[144:145], 2, v[148:149]
	s_nop 0
	v_lshl_add_u64 v[156:157], s[26:27], 0, v[156:157]
	v_lshl_add_u64 v[162:163], v[144:145], 1, v[156:157]
	v_lshl_add_u64 v[148:149], v[146:147], 2, s[8:9]
	v_lshlrev_b32_e32 v158, 13, v146
	v_lshl_add_u32 v158, v144, 2, v158
	v_lshlrev_b32_e32 v159, 12, v146
	v_lshl_add_u32 v159, v144, 1, v159
	s_nop 0
	v_mov_b32_e32 v200, v158
	v_mov_b32_e32 v163, v159
	global_load_dwordx4 v[176:179], v200, s[28:29]
	global_load_dwordx4 v[180:183], v200, s[28:29] offset:16
	global_load_dwordx4 v[184:187], v200, s[28:29] offset:512
	global_load_dwordx4 v[188:191], v200, s[28:29] offset:528
	v_add_u32_e32 v201, 0x20000, v158
	v_add_u32_e32 v174, 0x10000, v159
	global_load_dwordx4 v[192:195], v201, s[28:29]
	global_load_dwordx4 v[196:199], v201, s[28:29] offset:16
	global_load_dwordx4 v[216:219], v201, s[28:29] offset:512
	global_load_dwordx4 v[220:223], v201, s[28:29] offset:528
	v_add_u32_e32 v162, 0x40000, v158
	v_add_u32_e32 v175, 0x20000, v159
	global_load_dwordx4 v[224:227], v162, s[28:29]
	global_load_dwordx4 v[228:231], v162, s[28:29] offset:16
	global_load_dwordx4 v[232:235], v162, s[28:29] offset:512
	global_load_dwordx4 v[166:169], v162, s[28:29] offset:528
	s_waitcnt vmcnt(8)
	v_pk_add_f32 v[176:177], v[128:129], v[176:177]
	v_pk_add_f32 v[178:179], v[130:131], v[178:179]
	v_pk_add_f32 v[180:181], v[124:125], v[180:181]
	v_pk_add_f32 v[182:183], v[126:127], v[182:183]
	global_store_dwordx4 v200, v[176:179], s[28:29]
	global_store_dwordx4 v200, v[180:183], s[28:29] offset:16
	v_cvt_pk_bf16_f32 v170, v176, v177
	v_cvt_pk_bf16_f32 v171, v178, v179
	v_cvt_pk_bf16_f32 v172, v180, v181
	v_cvt_pk_bf16_f32 v173, v182, v183
	global_store_dwordx4 v163, v[170:173], s[26:27]
	v_mul_f32_e32 v155, v177, v177
	v_mul_f32_e32 v156, v179, v179
	v_fmac_f32_e32 v155, v176, v176
	v_fmac_f32_e32 v156, v178, v178
	v_add_f32_e32 v155, v155, v156
	v_mul_f32_e32 v156, v181, v181
	v_fmac_f32_e32 v156, v180, v180
	v_add_f32_e32 v155, v155, v156
	v_mul_f32_e32 v156, v183, v183
	v_fmac_f32_e32 v156, v182, v182
	v_add_f32_e32 v155, v156, v155
	v_pk_add_f32 v[184:185], v[112:113], v[184:185]
	v_pk_add_f32 v[186:187], v[114:115], v[186:187]
	v_pk_add_f32 v[188:189], v[104:105], v[188:189]
	v_pk_add_f32 v[190:191], v[106:107], v[190:191]
	global_store_dwordx4 v200, v[184:187], s[28:29] offset:512
	global_store_dwordx4 v200, v[188:191], s[28:29] offset:528
	v_cvt_pk_bf16_f32 v170, v184, v185
	v_cvt_pk_bf16_f32 v171, v186, v187
	v_cvt_pk_bf16_f32 v172, v188, v189
	v_cvt_pk_bf16_f32 v173, v190, v191
	global_store_dwordx4 v163, v[170:173], s[26:27] offset:256
	v_mul_f32_e32 v161, v185, v185
	v_mul_f32_e32 v156, v187, v187
	v_fmac_f32_e32 v161, v184, v184
	v_fmac_f32_e32 v156, v186, v186
	v_add_f32_e32 v161, v161, v156
	v_mul_f32_e32 v156, v189, v189
	v_fmac_f32_e32 v156, v188, v188
	v_add_f32_e32 v161, v161, v156
	v_mul_f32_e32 v156, v191, v191
	v_fmac_f32_e32 v156, v190, v190
	v_add_f32_e32 v161, v156, v161
	v_add_f32_e32 v147, v155, v161
	ds_bpermute_b32 v156, v154, v147
	s_waitcnt lgkmcnt(0)
	v_add_f32_e32 v147, v147, v156
	ds_bpermute_b32 v156, v153, v147
	v_add_u32_e32 v200, 0x60000, v158
	v_add_u32_e32 v163, 0x30000, v159
	global_load_dwordx4 v[176:179], v200, s[28:29]
	global_load_dwordx4 v[180:183], v200, s[28:29] offset:16
	global_load_dwordx4 v[184:187], v200, s[28:29] offset:512
	global_load_dwordx4 v[188:191], v200, s[28:29] offset:528
	s_and_saveexec_b64 s[22:23], s[38:39]
	s_cbranch_execz .Lepi_out_skip0
	s_waitcnt lgkmcnt(0)
	v_add_f32_e32 v147, v147, v156
	global_atomic_add_f32 v[148:149], v147, off
.Lepi_out_skip0:
	s_or_b64 exec, exec, s[22:23]
	s_waitcnt lgkmcnt(0)
	s_waitcnt vmcnt(14)
	v_pk_add_f32 v[192:193], v[120:121], v[192:193]
	v_pk_add_f32 v[194:195], v[122:123], v[194:195]
	v_pk_add_f32 v[196:197], v[116:117], v[196:197]
	v_pk_add_f32 v[198:199], v[118:119], v[198:199]
	global_store_dwordx4 v201, v[192:195], s[28:29]
	global_store_dwordx4 v201, v[196:199], s[28:29] offset:16
	v_cvt_pk_bf16_f32 v170, v192, v193
	v_cvt_pk_bf16_f32 v171, v194, v195
	v_cvt_pk_bf16_f32 v172, v196, v197
	v_cvt_pk_bf16_f32 v173, v198, v199
	global_store_dwordx4 v174, v[170:173], s[26:27]
	v_mul_f32_e32 v155, v193, v193
	v_mul_f32_e32 v156, v195, v195
	v_fmac_f32_e32 v155, v192, v192
	v_fmac_f32_e32 v156, v194, v194
	v_add_f32_e32 v155, v155, v156
	v_mul_f32_e32 v156, v197, v197
	v_fmac_f32_e32 v156, v196, v196
	v_add_f32_e32 v155, v155, v156
	v_mul_f32_e32 v156, v199, v199
	v_fmac_f32_e32 v156, v198, v198
	v_add_f32_e32 v155, v156, v155
	v_pk_add_f32 v[216:217], v[96:97], v[216:217]
	v_pk_add_f32 v[218:219], v[98:99], v[218:219]
	v_pk_add_f32 v[220:221], v[88:89], v[220:221]
	v_pk_add_f32 v[222:223], v[90:91], v[222:223]
	global_store_dwordx4 v201, v[216:219], s[28:29] offset:512
	global_store_dwordx4 v201, v[220:223], s[28:29] offset:528
	v_cvt_pk_bf16_f32 v170, v216, v217
	v_cvt_pk_bf16_f32 v171, v218, v219
	v_cvt_pk_bf16_f32 v172, v220, v221
	v_cvt_pk_bf16_f32 v173, v222, v223
	global_store_dwordx4 v174, v[170:173], s[26:27] offset:256
	v_mul_f32_e32 v161, v217, v217
	v_mul_f32_e32 v156, v219, v219
	v_fmac_f32_e32 v161, v216, v216
	v_fmac_f32_e32 v156, v218, v218
	v_add_f32_e32 v161, v161, v156
	v_mul_f32_e32 v156, v221, v221
	v_fmac_f32_e32 v156, v220, v220
	v_add_f32_e32 v161, v161, v156
	v_mul_f32_e32 v156, v223, v223
	v_fmac_f32_e32 v156, v222, v222
	v_add_f32_e32 v161, v156, v161
	v_add_f32_e32 v147, v155, v161
	ds_bpermute_b32 v156, v154, v147
	s_waitcnt lgkmcnt(0)
	v_add_f32_e32 v147, v147, v156
	ds_bpermute_b32 v156, v153, v147
	v_add_u32_e32 v201, 0x100000, v158
	v_add_u32_e32 v174, 0x80000, v159
	global_load_dwordx4 v[192:195], v201, s[28:29]
	global_load_dwordx4 v[196:199], v201, s[28:29] offset:16
	global_load_dwordx4 v[216:219], v201, s[28:29] offset:512
	global_load_dwordx4 v[220:223], v201, s[28:29] offset:528
	s_and_saveexec_b64 s[22:23], s[38:39]
	s_cbranch_execz .Lepi_out_skip1
	s_waitcnt lgkmcnt(0)
	v_add_f32_e32 v147, v147, v156
	global_atomic_add_f32 v[148:149], v147, off offset:64
.Lepi_out_skip1:
	s_or_b64 exec, exec, s[22:23]
	s_waitcnt lgkmcnt(0)
	s_waitcnt vmcnt(20)
	v_pk_add_f32 v[224:225], v[108:109], v[224:225]
	v_pk_add_f32 v[226:227], v[110:111], v[226:227]
	v_pk_add_f32 v[228:229], v[100:101], v[228:229]
	v_pk_add_f32 v[230:231], v[102:103], v[230:231]
	global_store_dwordx4 v162, v[224:227], s[28:29]
	global_store_dwordx4 v162, v[228:231], s[28:29] offset:16
	v_cvt_pk_bf16_f32 v170, v224, v225
	v_cvt_pk_bf16_f32 v171, v226, v227
	v_cvt_pk_bf16_f32 v172, v228, v229
	v_cvt_pk_bf16_f32 v173, v230, v231
	global_store_dwordx4 v175, v[170:173], s[26:27]
	v_mul_f32_e32 v155, v225, v225
	v_mul_f32_e32 v156, v227, v227
	v_fmac_f32_e32 v155, v224, v224
	v_fmac_f32_e32 v156, v226, v226
	v_add_f32_e32 v155, v155, v156
	v_mul_f32_e32 v156, v229, v229
	v_fmac_f32_e32 v156, v228, v228
	v_add_f32_e32 v155, v155, v156
	v_mul_f32_e32 v156, v231, v231
	v_fmac_f32_e32 v156, v230, v230
	v_add_f32_e32 v155, v156, v155
	v_pk_add_f32 v[232:233], v[80:81], v[232:233]
	v_pk_add_f32 v[234:235], v[82:83], v[234:235]
	v_pk_add_f32 v[166:167], v[76:77], v[166:167]
	v_pk_add_f32 v[168:169], v[78:79], v[168:169]
	global_store_dwordx4 v162, v[232:235], s[28:29] offset:512
	global_store_dwordx4 v162, v[166:169], s[28:29] offset:528
	v_cvt_pk_bf16_f32 v170, v232, v233
	v_cvt_pk_bf16_f32 v171, v234, v235
	v_cvt_pk_bf16_f32 v172, v166, v167
	v_cvt_pk_bf16_f32 v173, v168, v169
	global_store_dwordx4 v175, v[170:173], s[26:27] offset:256
	v_mul_f32_e32 v161, v233, v233
	v_mul_f32_e32 v156, v235, v235
	v_fmac_f32_e32 v161, v232, v232
	v_fmac_f32_e32 v156, v234, v234
	v_add_f32_e32 v161, v161, v156
	v_mul_f32_e32 v156, v167, v167
	v_fmac_f32_e32 v156, v166, v166
	v_add_f32_e32 v161, v161, v156
	v_mul_f32_e32 v156, v169, v169
	v_fmac_f32_e32 v156, v168, v168
	v_add_f32_e32 v161, v156, v161
	v_add_f32_e32 v147, v155, v161
	ds_bpermute_b32 v156, v154, v147
	s_waitcnt lgkmcnt(0)
	v_add_f32_e32 v147, v147, v156
	ds_bpermute_b32 v156, v153, v147
	v_add_u32_e32 v162, 0x120000, v158
	v_add_u32_e32 v175, 0x90000, v159
	global_load_dwordx4 v[224:227], v162, s[28:29]
	global_load_dwordx4 v[228:231], v162, s[28:29] offset:16
	global_load_dwordx4 v[232:235], v162, s[28:29] offset:512
	global_load_dwordx4 v[166:169], v162, s[28:29] offset:528
	s_and_saveexec_b64 s[22:23], s[38:39]
	s_cbranch_execz .Lepi_out_skip2
	s_waitcnt lgkmcnt(0)
	v_add_f32_e32 v147, v147, v156
	global_atomic_add_f32 v[148:149], v147, off offset:128
.Lepi_out_skip2:
	s_or_b64 exec, exec, s[22:23]
	s_waitcnt lgkmcnt(0)
	s_waitcnt vmcnt(20)
	v_pk_add_f32 v[176:177], v[92:93], v[176:177]
	v_pk_add_f32 v[178:179], v[94:95], v[178:179]
	v_pk_add_f32 v[180:181], v[84:85], v[180:181]
	v_pk_add_f32 v[182:183], v[86:87], v[182:183]
	global_store_dwordx4 v200, v[176:179], s[28:29]
	global_store_dwordx4 v200, v[180:183], s[28:29] offset:16
	v_cvt_pk_bf16_f32 v170, v176, v177
	v_cvt_pk_bf16_f32 v171, v178, v179
	v_cvt_pk_bf16_f32 v172, v180, v181
	v_cvt_pk_bf16_f32 v173, v182, v183
	global_store_dwordx4 v163, v[170:173], s[26:27]
	v_mul_f32_e32 v155, v177, v177
	v_mul_f32_e32 v156, v179, v179
	v_fmac_f32_e32 v155, v176, v176
	v_fmac_f32_e32 v156, v178, v178
	v_add_f32_e32 v155, v155, v156
	v_mul_f32_e32 v156, v181, v181
	v_fmac_f32_e32 v156, v180, v180
	v_add_f32_e32 v155, v155, v156
	v_mul_f32_e32 v156, v183, v183
	v_fmac_f32_e32 v156, v182, v182
	v_add_f32_e32 v155, v156, v155
	v_pk_add_f32 v[184:185], v[72:73], v[184:185]
	v_pk_add_f32 v[186:187], v[74:75], v[186:187]
	v_pk_add_f32 v[188:189], v[68:69], v[188:189]
	v_pk_add_f32 v[190:191], v[70:71], v[190:191]
	global_store_dwordx4 v200, v[184:187], s[28:29] offset:512
	global_store_dwordx4 v200, v[188:191], s[28:29] offset:528
	v_cvt_pk_bf16_f32 v170, v184, v185
	v_cvt_pk_bf16_f32 v171, v186, v187
	v_cvt_pk_bf16_f32 v172, v188, v189
	v_cvt_pk_bf16_f32 v173, v190, v191
	global_store_dwordx4 v163, v[170:173], s[26:27] offset:256
	v_mul_f32_e32 v161, v185, v185
	v_mul_f32_e32 v156, v187, v187
	v_fmac_f32_e32 v161, v184, v184
	v_fmac_f32_e32 v156, v186, v186
	v_add_f32_e32 v161, v161, v156
	v_mul_f32_e32 v156, v189, v189
	v_fmac_f32_e32 v156, v188, v188
	v_add_f32_e32 v161, v161, v156
	v_mul_f32_e32 v156, v191, v191
	v_fmac_f32_e32 v156, v190, v190
	v_add_f32_e32 v161, v156, v161
	v_add_f32_e32 v147, v155, v161
	ds_bpermute_b32 v156, v154, v147
	s_waitcnt lgkmcnt(0)
	v_add_f32_e32 v147, v147, v156
	ds_bpermute_b32 v156, v153, v147
	v_add_u32_e32 v200, 0x140000, v158
	v_add_u32_e32 v163, 0xa0000, v159
	global_load_dwordx4 v[176:179], v200, s[28:29]
	global_load_dwordx4 v[180:183], v200, s[28:29] offset:16
	global_load_dwordx4 v[184:187], v200, s[28:29] offset:512
	global_load_dwordx4 v[188:191], v200, s[28:29] offset:528
	s_and_saveexec_b64 s[22:23], s[38:39]
	s_cbranch_execz .Lepi_out_skip3
	s_waitcnt lgkmcnt(0)
	v_add_f32_e32 v147, v147, v156
	global_atomic_add_f32 v[148:149], v147, off offset:192
.Lepi_out_skip3:
	s_or_b64 exec, exec, s[22:23]
	s_waitcnt lgkmcnt(0)
	s_waitcnt vmcnt(20)
	v_pk_add_f32 v[192:193], v[64:65], v[192:193]
	v_pk_add_f32 v[194:195], v[66:67], v[194:195]
	v_pk_add_f32 v[196:197], v[60:61], v[196:197]
	v_pk_add_f32 v[198:199], v[62:63], v[198:199]
	global_store_dwordx4 v201, v[192:195], s[28:29]
	global_store_dwordx4 v201, v[196:199], s[28:29] offset:16
	v_cvt_pk_bf16_f32 v170, v192, v193
	v_cvt_pk_bf16_f32 v171, v194, v195
	v_cvt_pk_bf16_f32 v172, v196, v197
	v_cvt_pk_bf16_f32 v173, v198, v199
	global_store_dwordx4 v174, v[170:173], s[26:27]
	v_mul_f32_e32 v155, v193, v193
	v_mul_f32_e32 v156, v195, v195
	v_fmac_f32_e32 v155, v192, v192
	v_fmac_f32_e32 v156, v194, v194
	v_add_f32_e32 v155, v155, v156
	v_mul_f32_e32 v156, v197, v197
	v_fmac_f32_e32 v156, v196, v196
	v_add_f32_e32 v155, v155, v156
	v_mul_f32_e32 v156, v199, v199
	v_fmac_f32_e32 v156, v198, v198
	v_add_f32_e32 v155, v156, v155
	v_pk_add_f32 v[216:217], v[48:49], v[216:217]
	v_pk_add_f32 v[218:219], v[50:51], v[218:219]
	v_pk_add_f32 v[220:221], v[40:41], v[220:221]
	v_pk_add_f32 v[222:223], v[42:43], v[222:223]
	global_store_dwordx4 v201, v[216:219], s[28:29] offset:512
	global_store_dwordx4 v201, v[220:223], s[28:29] offset:528
	v_cvt_pk_bf16_f32 v170, v216, v217
	v_cvt_pk_bf16_f32 v171, v218, v219
	v_cvt_pk_bf16_f32 v172, v220, v221
	v_cvt_pk_bf16_f32 v173, v222, v223
	global_store_dwordx4 v174, v[170:173], s[26:27] offset:256
	v_mul_f32_e32 v161, v217, v217
	v_mul_f32_e32 v156, v219, v219
	v_fmac_f32_e32 v161, v216, v216
	v_fmac_f32_e32 v156, v218, v218
	v_add_f32_e32 v161, v161, v156
	v_mul_f32_e32 v156, v221, v221
	v_fmac_f32_e32 v156, v220, v220
	v_add_f32_e32 v161, v161, v156
	v_mul_f32_e32 v156, v223, v223
	v_fmac_f32_e32 v156, v222, v222
	v_add_f32_e32 v161, v156, v161
	v_add_f32_e32 v147, v155, v161
	ds_bpermute_b32 v156, v154, v147
	s_waitcnt lgkmcnt(0)
	v_add_f32_e32 v147, v147, v156
	ds_bpermute_b32 v156, v153, v147
	v_add_u32_e32 v201, 0x160000, v158
	v_add_u32_e32 v174, 0xb0000, v159
	global_load_dwordx4 v[192:195], v201, s[28:29]
	global_load_dwordx4 v[196:199], v201, s[28:29] offset:16
	global_load_dwordx4 v[216:219], v201, s[28:29] offset:512
	global_load_dwordx4 v[220:223], v201, s[28:29] offset:528
	s_and_saveexec_b64 s[22:23], s[38:39]
	s_cbranch_execz .Lepi_out_skip4
	s_waitcnt lgkmcnt(0)
	v_add_f32_e32 v147, v147, v156
	global_atomic_add_f32 v[148:149], v147, off offset:512
.Lepi_out_skip4:
	s_or_b64 exec, exec, s[22:23]
	s_waitcnt lgkmcnt(0)
	s_waitcnt vmcnt(20)
	v_pk_add_f32 v[224:225], v[56:57], v[224:225]
	v_pk_add_f32 v[226:227], v[58:59], v[226:227]
	v_pk_add_f32 v[228:229], v[52:53], v[228:229]
	v_pk_add_f32 v[230:231], v[54:55], v[230:231]
	global_store_dwordx4 v162, v[224:227], s[28:29]
	global_store_dwordx4 v162, v[228:231], s[28:29] offset:16
	v_cvt_pk_bf16_f32 v170, v224, v225
	v_cvt_pk_bf16_f32 v171, v226, v227
	v_cvt_pk_bf16_f32 v172, v228, v229
	v_cvt_pk_bf16_f32 v173, v230, v231
	global_store_dwordx4 v175, v[170:173], s[26:27]
	v_mul_f32_e32 v155, v225, v225
	v_mul_f32_e32 v156, v227, v227
	v_fmac_f32_e32 v155, v224, v224
	v_fmac_f32_e32 v156, v226, v226
	v_add_f32_e32 v155, v155, v156
	v_mul_f32_e32 v156, v229, v229
	v_fmac_f32_e32 v156, v228, v228
	v_add_f32_e32 v155, v155, v156
	v_mul_f32_e32 v156, v231, v231
	v_fmac_f32_e32 v156, v230, v230
	v_add_f32_e32 v155, v156, v155
	v_pk_add_f32 v[232:233], v[32:33], v[232:233]
	v_pk_add_f32 v[234:235], v[34:35], v[234:235]
	v_pk_add_f32 v[166:167], v[24:25], v[166:167]
	v_pk_add_f32 v[168:169], v[26:27], v[168:169]
	global_store_dwordx4 v162, v[232:235], s[28:29] offset:512
	global_store_dwordx4 v162, v[166:169], s[28:29] offset:528
	v_cvt_pk_bf16_f32 v170, v232, v233
	v_cvt_pk_bf16_f32 v171, v234, v235
	v_cvt_pk_bf16_f32 v172, v166, v167
	v_cvt_pk_bf16_f32 v173, v168, v169
	global_store_dwordx4 v175, v[170:173], s[26:27] offset:256
	v_mul_f32_e32 v161, v233, v233
	v_mul_f32_e32 v156, v235, v235
	v_fmac_f32_e32 v161, v232, v232
	v_fmac_f32_e32 v156, v234, v234
	v_add_f32_e32 v161, v161, v156
	v_mul_f32_e32 v156, v167, v167
	v_fmac_f32_e32 v156, v166, v166
	v_add_f32_e32 v161, v161, v156
	v_mul_f32_e32 v156, v169, v169
	v_fmac_f32_e32 v156, v168, v168
	v_add_f32_e32 v161, v156, v161
	v_add_f32_e32 v147, v155, v161
	ds_bpermute_b32 v156, v154, v147
	s_waitcnt lgkmcnt(0)
	v_add_f32_e32 v147, v147, v156
	ds_bpermute_b32 v156, v153, v147
	s_and_saveexec_b64 s[22:23], s[38:39]
	s_cbranch_execz .Lepi_out_skip5
	s_waitcnt lgkmcnt(0)
	v_add_f32_e32 v147, v147, v156
	global_atomic_add_f32 v[148:149], v147, off offset:576
.Lepi_out_skip5:
	s_or_b64 exec, exec, s[22:23]
	s_waitcnt lgkmcnt(0)
	s_waitcnt vmcnt(16)
	v_pk_add_f32 v[176:177], v[44:45], v[176:177]
	v_pk_add_f32 v[178:179], v[46:47], v[178:179]
	v_pk_add_f32 v[180:181], v[36:37], v[180:181]
	v_pk_add_f32 v[182:183], v[38:39], v[182:183]
	global_store_dwordx4 v200, v[176:179], s[28:29]
	global_store_dwordx4 v200, v[180:183], s[28:29] offset:16
	v_cvt_pk_bf16_f32 v170, v176, v177
	v_cvt_pk_bf16_f32 v171, v178, v179
	v_cvt_pk_bf16_f32 v172, v180, v181
	v_cvt_pk_bf16_f32 v173, v182, v183
	global_store_dwordx4 v163, v[170:173], s[26:27]
	v_mul_f32_e32 v155, v177, v177
	v_mul_f32_e32 v156, v179, v179
	v_fmac_f32_e32 v155, v176, v176
	v_fmac_f32_e32 v156, v178, v178
	v_add_f32_e32 v155, v155, v156
	v_mul_f32_e32 v156, v181, v181
	v_fmac_f32_e32 v156, v180, v180
	v_add_f32_e32 v155, v155, v156
	v_mul_f32_e32 v156, v183, v183
	v_fmac_f32_e32 v156, v182, v182
	v_add_f32_e32 v155, v156, v155
	v_pk_add_f32 v[184:185], v[16:17], v[184:185]
	v_pk_add_f32 v[186:187], v[18:19], v[186:187]
	v_pk_add_f32 v[188:189], v[12:13], v[188:189]
	v_pk_add_f32 v[190:191], v[14:15], v[190:191]
	global_store_dwordx4 v200, v[184:187], s[28:29] offset:512
	global_store_dwordx4 v200, v[188:191], s[28:29] offset:528
	v_cvt_pk_bf16_f32 v170, v184, v185
	v_cvt_pk_bf16_f32 v171, v186, v187
	v_cvt_pk_bf16_f32 v172, v188, v189
	v_cvt_pk_bf16_f32 v173, v190, v191
	global_store_dwordx4 v163, v[170:173], s[26:27] offset:256
	v_mul_f32_e32 v161, v185, v185
	v_mul_f32_e32 v156, v187, v187
	v_fmac_f32_e32 v161, v184, v184
	v_fmac_f32_e32 v156, v186, v186
	v_add_f32_e32 v161, v161, v156
	v_mul_f32_e32 v156, v189, v189
	v_fmac_f32_e32 v156, v188, v188
	v_add_f32_e32 v161, v161, v156
	v_mul_f32_e32 v156, v191, v191
	v_fmac_f32_e32 v156, v190, v190
	v_add_f32_e32 v161, v156, v161
	v_add_f32_e32 v147, v155, v161
	ds_bpermute_b32 v156, v154, v147
	s_waitcnt lgkmcnt(0)
	v_add_f32_e32 v147, v147, v156
	ds_bpermute_b32 v156, v153, v147
	s_and_saveexec_b64 s[22:23], s[38:39]
	s_cbranch_execz .Lepi_out_skip6
	s_waitcnt lgkmcnt(0)
	v_add_f32_e32 v147, v147, v156
	global_atomic_add_f32 v[148:149], v147, off offset:640
.Lepi_out_skip6:
	s_or_b64 exec, exec, s[22:23]
	s_waitcnt lgkmcnt(0)
	s_waitcnt vmcnt(12)
	v_pk_add_f32 v[192:193], v[28:29], v[192:193]
	v_pk_add_f32 v[194:195], v[30:31], v[194:195]
	v_pk_add_f32 v[196:197], v[20:21], v[196:197]
	v_pk_add_f32 v[198:199], v[22:23], v[198:199]
	global_store_dwordx4 v201, v[192:195], s[28:29]
	global_store_dwordx4 v201, v[196:199], s[28:29] offset:16
	v_cvt_pk_bf16_f32 v170, v192, v193
	v_cvt_pk_bf16_f32 v171, v194, v195
	v_cvt_pk_bf16_f32 v172, v196, v197
	v_cvt_pk_bf16_f32 v173, v198, v199
	global_store_dwordx4 v174, v[170:173], s[26:27]
	v_mul_f32_e32 v155, v193, v193
	v_mul_f32_e32 v156, v195, v195
	v_fmac_f32_e32 v155, v192, v192
	v_fmac_f32_e32 v156, v194, v194
	v_add_f32_e32 v155, v155, v156
	v_mul_f32_e32 v156, v197, v197
	v_fmac_f32_e32 v156, v196, v196
	v_add_f32_e32 v155, v155, v156
	v_mul_f32_e32 v156, v199, v199
	v_fmac_f32_e32 v156, v198, v198
	v_add_f32_e32 v155, v156, v155
	v_pk_add_f32 v[216:217], v[8:9], v[216:217]
	v_pk_add_f32 v[218:219], v[10:11], v[218:219]
	v_pk_add_f32 v[220:221], v[4:5], v[220:221]
	v_pk_add_f32 v[222:223], v[6:7], v[222:223]
	global_store_dwordx4 v201, v[216:219], s[28:29] offset:512
	global_store_dwordx4 v201, v[220:223], s[28:29] offset:528
	v_cvt_pk_bf16_f32 v170, v216, v217
	v_cvt_pk_bf16_f32 v171, v218, v219
	v_cvt_pk_bf16_f32 v172, v220, v221
	v_cvt_pk_bf16_f32 v173, v222, v223
	global_store_dwordx4 v174, v[170:173], s[26:27] offset:256
	v_mul_f32_e32 v161, v217, v217
	v_mul_f32_e32 v156, v219, v219
	v_fmac_f32_e32 v161, v216, v216
	v_fmac_f32_e32 v156, v218, v218
	v_add_f32_e32 v161, v161, v156
	v_mul_f32_e32 v156, v221, v221
	v_fmac_f32_e32 v156, v220, v220
	v_add_f32_e32 v161, v161, v156
	v_mul_f32_e32 v156, v223, v223
	v_fmac_f32_e32 v156, v222, v222
	v_add_f32_e32 v161, v156, v161
	v_add_f32_e32 v147, v155, v161
	ds_bpermute_b32 v156, v154, v147
	s_waitcnt lgkmcnt(0)
	v_add_f32_e32 v147, v147, v156
	ds_bpermute_b32 v156, v153, v147
	s_and_saveexec_b64 s[22:23], s[38:39]
	s_cbranch_execz .Lepi_out_skip7
	s_waitcnt lgkmcnt(0)
	v_add_f32_e32 v147, v147, v156
	global_atomic_add_f32 v[148:149], v147, off offset:704
.Lepi_out_skip7:
	s_or_b64 exec, exec, s[22:23]
	s_waitcnt lgkmcnt(0)
.LBB0_269:
	s_or_b64 exec, exec, s[22:23]
	s_mov_b64 s[22:23], 0

.LBB0_535:
.LBB0_536:
	s_ashr_i32 s0, s8, 8
	s_and_b32 s0, s0, 0xffffff8
	s_or_b32 s0, s0, s11
	s_lshl_b32 s0, s0, 4
	s_ashr_i32 s5, s8, 3
	s_ashr_i32 s1, s0, 31
	s_add_i32 s4, s5, 0x2000
	s_lshl_b64 s[0:1], s[0:1], 18
	s_add_u32 s0, s64, s0
	s_addc_u32 s1, s65, s1
	s_lshl_b32 s5, s5, 10
	s_and_b32 s5, s5, 0x3fc00
	s_add_u32 s0, s0, s5
	s_addc_u32 s1, s1, 0
	s_mov_b32 s5, 0
	s_lshl_b64 s[6:7], s[4:5], 13
	v_lshl_add_u64 v[82:83], v[0:1], 0, s[6:7]
	global_load_dwordx4 v[14:17], v6, s[0:1]
	global_load_dwordx4 v[18:21], v[82:83], off
	s_add_u32 s0, s0, 0x40000
	s_addc_u32 s1, s1, 0
	global_load_dwordx4 v[22:25], v6, s[0:1]
	s_add_u32 s0, s0, 0x40000
	s_addc_u32 s1, s1, 0
	global_load_dwordx4 v[26:29], v6, s[0:1]
	s_add_u32 s0, s0, 0x40000
	s_addc_u32 s1, s1, 0
	global_load_dwordx4 v[30:33], v6, s[0:1]
	s_add_u32 s0, s0, 0x40000
	s_addc_u32 s1, s1, 0
	global_load_dwordx4 v[34:37], v6, s[0:1]
	s_add_u32 s0, s0, 0x40000
	s_addc_u32 s1, s1, 0
	global_load_dwordx4 v[38:41], v6, s[0:1]
	s_add_u32 s0, s0, 0x40000
	s_addc_u32 s1, s1, 0
	global_load_dwordx4 v[42:45], v6, s[0:1]
	s_add_u32 s0, s0, 0x40000
	s_addc_u32 s1, s1, 0
	global_load_dwordx4 v[46:49], v6, s[0:1]
	s_add_u32 s0, s0, 0x40000
	s_addc_u32 s1, s1, 0
	global_load_dwordx4 v[50:53], v6, s[0:1]
	s_add_u32 s0, s0, 0x40000
	s_addc_u32 s1, s1, 0
	global_load_dwordx4 v[54:57], v6, s[0:1]
	s_add_u32 s0, s0, 0x40000
	s_addc_u32 s1, s1, 0
	global_load_dwordx4 v[58:61], v6, s[0:1]
	s_add_u32 s0, s0, 0x40000
	s_addc_u32 s1, s1, 0
	global_load_dwordx4 v[62:65], v6, s[0:1]
	s_add_u32 s0, s0, 0x40000
	s_addc_u32 s1, s1, 0
	global_load_dwordx4 v[66:69], v6, s[0:1]
	s_add_u32 s0, s0, 0x40000
	s_addc_u32 s1, s1, 0
	global_load_dwordx4 v[70:73], v6, s[0:1]
	s_add_u32 s0, s0, 0x40000
	s_addc_u32 s1, s1, 0
	global_load_dwordx4 v[74:77], v6, s[0:1]
	s_add_u32 s0, s0, 0x40000
	s_addc_u32 s1, s1, 0
	global_load_dwordx4 v[78:81], v6, s[0:1]
	s_add_i32 s12, s8, s44
	s_cmpk_gt_i32 s12, 0x9ff
	s_cbranch_scc1 .Lrd1_single
	s_add_u32 s0, s0, 0x1c40000
	s_addc_u32 s1, s1, 0
	s_mov_b32 s12, 0x200000
	s_mov_b32 s13, 0
	v_lshl_add_u64 v[154:155], v[82:83], 0, s[12:13]
	global_load_dwordx4 v[86:89], v6, s[0:1]
	global_load_dwordx4 v[90:93], v[154:155], off
	s_add_u32 s0, s0, 0x40000
	s_addc_u32 s1, s1, 0
	global_load_dwordx4 v[94:97], v6, s[0:1]
	s_add_u32 s0, s0, 0x40000
	s_addc_u32 s1, s1, 0
	global_load_dwordx4 v[98:101], v6, s[0:1]
	s_add_u32 s0, s0, 0x40000
	s_addc_u32 s1, s1, 0
	global_load_dwordx4 v[102:105], v6, s[0:1]
	s_add_u32 s0, s0, 0x40000
	s_addc_u32 s1, s1, 0
	global_load_dwordx4 v[106:109], v6, s[0:1]
	s_add_u32 s0, s0, 0x40000
	s_addc_u32 s1, s1, 0
	global_load_dwordx4 v[110:113], v6, s[0:1]
	s_add_u32 s0, s0, 0x40000
	s_addc_u32 s1, s1, 0
	global_load_dwordx4 v[114:117], v6, s[0:1]
	s_add_u32 s0, s0, 0x40000
	s_addc_u32 s1, s1, 0
	global_load_dwordx4 v[118:121], v6, s[0:1]
	s_add_u32 s0, s0, 0x40000
	s_addc_u32 s1, s1, 0
	global_load_dwordx4 v[122:125], v6, s[0:1]
	s_add_u32 s0, s0, 0x40000
	s_addc_u32 s1, s1, 0
	global_load_dwordx4 v[126:129], v6, s[0:1]
	s_add_u32 s0, s0, 0x40000
	s_addc_u32 s1, s1, 0
	global_load_dwordx4 v[130:133], v6, s[0:1]
	s_add_u32 s0, s0, 0x40000
	s_addc_u32 s1, s1, 0
	global_load_dwordx4 v[134:137], v6, s[0:1]
	s_add_u32 s0, s0, 0x40000
	s_addc_u32 s1, s1, 0
	global_load_dwordx4 v[138:141], v6, s[0:1]
	s_add_u32 s0, s0, 0x40000
	s_addc_u32 s1, s1, 0
	global_load_dwordx4 v[142:145], v6, s[0:1]
	s_add_u32 s0, s0, 0x40000
	s_addc_u32 s1, s1, 0
	global_load_dwordx4 v[146:149], v6, s[0:1]
	s_add_u32 s0, s0, 0x40000
	s_addc_u32 s1, s1, 0
	global_load_dwordx4 v[150:153], v6, s[0:1]
	s_waitcnt vmcnt(17)
	v_pk_add_f32 v[16:17], v[20:21], v[16:17]
	v_pk_add_f32 v[14:15], v[18:19], v[14:15]
	v_pk_add_f32 v[16:17], v[16:17], v[24:25]
	v_pk_add_f32 v[14:15], v[14:15], v[22:23]
	v_pk_add_f32 v[16:17], v[16:17], v[28:29]
	v_pk_add_f32 v[14:15], v[14:15], v[26:27]
	v_pk_add_f32 v[16:17], v[16:17], v[32:33]
	v_pk_add_f32 v[14:15], v[14:15], v[30:31]
	v_pk_add_f32 v[16:17], v[16:17], v[36:37]
	v_pk_add_f32 v[14:15], v[14:15], v[34:35]
	v_pk_add_f32 v[16:17], v[16:17], v[40:41]
	v_pk_add_f32 v[14:15], v[14:15], v[38:39]
	v_pk_add_f32 v[16:17], v[16:17], v[44:45]
	v_pk_add_f32 v[14:15], v[14:15], v[42:43]
	v_pk_add_f32 v[16:17], v[16:17], v[48:49]
	v_pk_add_f32 v[14:15], v[14:15], v[46:47]
	v_pk_add_f32 v[16:17], v[16:17], v[52:53]
	v_pk_add_f32 v[14:15], v[14:15], v[50:51]
	v_pk_add_f32 v[16:17], v[16:17], v[56:57]
	v_pk_add_f32 v[14:15], v[14:15], v[54:55]
	v_pk_add_f32 v[16:17], v[16:17], v[60:61]
	v_pk_add_f32 v[14:15], v[14:15], v[58:59]
	v_pk_add_f32 v[16:17], v[16:17], v[64:65]
	v_pk_add_f32 v[14:15], v[14:15], v[62:63]
	v_pk_add_f32 v[16:17], v[16:17], v[68:69]
	v_pk_add_f32 v[14:15], v[14:15], v[66:67]
	v_pk_add_f32 v[16:17], v[16:17], v[72:73]
	v_pk_add_f32 v[14:15], v[14:15], v[70:71]
	v_pk_add_f32 v[16:17], v[16:17], v[76:77]
	v_pk_add_f32 v[14:15], v[14:15], v[74:75]
	v_pk_add_f32 v[16:17], v[16:17], v[80:81]
	v_pk_add_f32 v[14:15], v[14:15], v[78:79]
	v_mul_f32_e32 v13, v17, v17
	v_mul_f32_e32 v7, v15, v15
	v_fmac_f32_e32 v7, v14, v14
	v_fmac_f32_e32 v13, v16, v16
	v_add_f32_e32 v7, v7, v13
	ds_bpermute_b32 v13, v3, v7
	global_store_dwordx4 v[82:83], v[14:17], off
	s_waitcnt lgkmcnt(0)
	v_add_f32_e32 v7, v7, v13
	ds_bpermute_b32 v13, v8, v7
	v_cvt_pk_bf16_f32 v14, v14, v15
	v_cvt_pk_bf16_f32 v15, v16, v17
	s_lshl_b64 s[0:1], s[4:5], 12
	v_lshl_add_u64 v[16:17], v[4:5], 0, s[0:1]
	global_store_dwordx2 v[16:17], v[14:15], off
	s_waitcnt lgkmcnt(0)
	v_add_f32_e32 v7, v7, v13
	ds_bpermute_b32 v13, v9, v7
	s_waitcnt lgkmcnt(0)
	v_add_f32_e32 v7, v7, v13
	ds_bpermute_b32 v13, v10, v7
	s_waitcnt lgkmcnt(0)
	v_add_f32_e32 v7, v7, v13
	ds_bpermute_b32 v13, v11, v7
	s_waitcnt lgkmcnt(0)
	v_add_f32_e32 v7, v7, v13
	ds_bpermute_b32 v13, v12, v7
	s_and_saveexec_b64 s[6:7], vcc
	s_cbranch_execz .Lrd1_naa
	s_waitcnt lgkmcnt(0)
	v_add_f32_e32 v13, v7, v13
	s_lshl_b64 s[0:1], s[4:5], 2
	s_add_u32 s0, s9, s0
	s_addc_u32 s1, s10, s1
	global_atomic_add_f32 v2, v13, s[0:1]
.Lrd1_naa:
	s_or_b64 exec, exec, s[6:7]
	s_waitcnt lgkmcnt(0)
	s_add_i32 s4, s4, 0x100
	s_waitcnt vmcnt(2)
	v_pk_add_f32 v[88:89], v[92:93], v[88:89]
	v_pk_add_f32 v[86:87], v[90:91], v[86:87]
	v_pk_add_f32 v[88:89], v[88:89], v[96:97]
	v_pk_add_f32 v[86:87], v[86:87], v[94:95]
	v_pk_add_f32 v[88:89], v[88:89], v[100:101]
	v_pk_add_f32 v[86:87], v[86:87], v[98:99]
	v_pk_add_f32 v[88:89], v[88:89], v[104:105]
	v_pk_add_f32 v[86:87], v[86:87], v[102:103]
	v_pk_add_f32 v[88:89], v[88:89], v[108:109]
	v_pk_add_f32 v[86:87], v[86:87], v[106:107]
	v_pk_add_f32 v[88:89], v[88:89], v[112:113]
	v_pk_add_f32 v[86:87], v[86:87], v[110:111]
	v_pk_add_f32 v[88:89], v[88:89], v[116:117]
	v_pk_add_f32 v[86:87], v[86:87], v[114:115]
	v_pk_add_f32 v[88:89], v[88:89], v[120:121]
	v_pk_add_f32 v[86:87], v[86:87], v[118:119]
	v_pk_add_f32 v[88:89], v[88:89], v[124:125]
	v_pk_add_f32 v[86:87], v[86:87], v[122:123]
	v_pk_add_f32 v[88:89], v[88:89], v[128:129]
	v_pk_add_f32 v[86:87], v[86:87], v[126:127]
	v_pk_add_f32 v[88:89], v[88:89], v[132:133]
	v_pk_add_f32 v[86:87], v[86:87], v[130:131]
	v_pk_add_f32 v[88:89], v[88:89], v[136:137]
	v_pk_add_f32 v[86:87], v[86:87], v[134:135]
	v_pk_add_f32 v[88:89], v[88:89], v[140:141]
	v_pk_add_f32 v[86:87], v[86:87], v[138:139]
	v_pk_add_f32 v[88:89], v[88:89], v[144:145]
	v_pk_add_f32 v[86:87], v[86:87], v[142:143]
	v_pk_add_f32 v[88:89], v[88:89], v[148:149]
	v_pk_add_f32 v[86:87], v[86:87], v[146:147]
	v_pk_add_f32 v[88:89], v[88:89], v[152:153]
	v_pk_add_f32 v[86:87], v[86:87], v[150:151]
	v_mul_f32_e32 v13, v89, v89
	v_mul_f32_e32 v7, v87, v87
	v_fmac_f32_e32 v7, v86, v86
	v_fmac_f32_e32 v13, v88, v88
	v_add_f32_e32 v7, v7, v13
	ds_bpermute_b32 v13, v3, v7
	global_store_dwordx4 v[154:155], v[86:89], off
	s_waitcnt lgkmcnt(0)
	v_add_f32_e32 v7, v7, v13
	ds_bpermute_b32 v13, v8, v7
	v_cvt_pk_bf16_f32 v86, v86, v87
	v_cvt_pk_bf16_f32 v87, v88, v89
	s_lshl_b64 s[0:1], s[4:5], 12
	v_lshl_add_u64 v[88:89], v[4:5], 0, s[0:1]
	global_store_dwordx2 v[88:89], v[86:87], off
	s_waitcnt lgkmcnt(0)
	v_add_f32_e32 v7, v7, v13
	ds_bpermute_b32 v13, v9, v7
	s_waitcnt lgkmcnt(0)
	v_add_f32_e32 v7, v7, v13
	ds_bpermute_b32 v13, v10, v7
	s_waitcnt lgkmcnt(0)
	v_add_f32_e32 v7, v7, v13
	ds_bpermute_b32 v13, v11, v7
	s_waitcnt lgkmcnt(0)
	v_add_f32_e32 v7, v7, v13
	ds_bpermute_b32 v13, v12, v7
	s_and_saveexec_b64 s[6:7], vcc
	s_cbranch_execz .Lrd1_nab
	s_waitcnt lgkmcnt(0)
	v_add_f32_e32 v13, v7, v13
	s_lshl_b64 s[0:1], s[4:5], 2
	s_add_u32 s0, s9, s0
	s_addc_u32 s1, s10, s1
	global_atomic_add_f32 v2, v13, s[0:1]
.Lrd1_nab:
	s_or_b64 exec, exec, s[6:7]
	s_waitcnt lgkmcnt(0)
	s_add_i32 s8, s8, s44
	s_branch .Lrd1_next
.Lrd1_single:
	s_waitcnt vmcnt(0)
	v_pk_add_f32 v[16:17], v[20:21], v[16:17]
	v_pk_add_f32 v[14:15], v[18:19], v[14:15]
	v_pk_add_f32 v[16:17], v[16:17], v[24:25]
	v_pk_add_f32 v[14:15], v[14:15], v[22:23]
	v_pk_add_f32 v[16:17], v[16:17], v[28:29]
	v_pk_add_f32 v[14:15], v[14:15], v[26:27]
	v_pk_add_f32 v[16:17], v[16:17], v[32:33]
	v_pk_add_f32 v[14:15], v[14:15], v[30:31]
	v_pk_add_f32 v[16:17], v[16:17], v[36:37]
	v_pk_add_f32 v[14:15], v[14:15], v[34:35]
	v_pk_add_f32 v[16:17], v[16:17], v[40:41]
	v_pk_add_f32 v[14:15], v[14:15], v[38:39]
	v_pk_add_f32 v[16:17], v[16:17], v[44:45]
	v_pk_add_f32 v[14:15], v[14:15], v[42:43]
	v_pk_add_f32 v[16:17], v[16:17], v[48:49]
	v_pk_add_f32 v[14:15], v[14:15], v[46:47]
	v_pk_add_f32 v[16:17], v[16:17], v[52:53]
	v_pk_add_f32 v[14:15], v[14:15], v[50:51]
	v_pk_add_f32 v[16:17], v[16:17], v[56:57]
	v_pk_add_f32 v[14:15], v[14:15], v[54:55]
	v_pk_add_f32 v[16:17], v[16:17], v[60:61]
	v_pk_add_f32 v[14:15], v[14:15], v[58:59]
	v_pk_add_f32 v[16:17], v[16:17], v[64:65]
	v_pk_add_f32 v[14:15], v[14:15], v[62:63]
	v_pk_add_f32 v[16:17], v[16:17], v[68:69]
	v_pk_add_f32 v[14:15], v[14:15], v[66:67]
	v_pk_add_f32 v[16:17], v[16:17], v[72:73]
	v_pk_add_f32 v[14:15], v[14:15], v[70:71]
	v_pk_add_f32 v[16:17], v[16:17], v[76:77]
	v_pk_add_f32 v[14:15], v[14:15], v[74:75]
	v_pk_add_f32 v[16:17], v[16:17], v[80:81]
	v_pk_add_f32 v[14:15], v[14:15], v[78:79]
	v_mul_f32_e32 v13, v17, v17
	v_mul_f32_e32 v7, v15, v15
	v_fmac_f32_e32 v7, v14, v14
	v_fmac_f32_e32 v13, v16, v16
	v_add_f32_e32 v7, v7, v13
	ds_bpermute_b32 v13, v3, v7
	global_store_dwordx4 v[82:83], v[14:17], off
	s_waitcnt lgkmcnt(0)
	v_add_f32_e32 v7, v7, v13
	ds_bpermute_b32 v13, v8, v7
	v_cvt_pk_bf16_f32 v14, v14, v15
	v_cvt_pk_bf16_f32 v15, v16, v17
	s_lshl_b64 s[0:1], s[4:5], 12
	v_lshl_add_u64 v[16:17], v[4:5], 0, s[0:1]
	global_store_dwordx2 v[16:17], v[14:15], off
	s_waitcnt lgkmcnt(0)
	v_add_f32_e32 v7, v7, v13
	ds_bpermute_b32 v13, v9, v7
	s_waitcnt lgkmcnt(0)
	v_add_f32_e32 v7, v7, v13
	ds_bpermute_b32 v13, v10, v7
	s_waitcnt lgkmcnt(0)
	v_add_f32_e32 v7, v7, v13
	ds_bpermute_b32 v13, v11, v7
	s_waitcnt lgkmcnt(0)
	v_add_f32_e32 v7, v7, v13
	ds_bpermute_b32 v13, v12, v7
	s_and_saveexec_b64 s[6:7], vcc
	s_cbranch_execz .Lrd1_nac
	s_waitcnt lgkmcnt(0)
	v_add_f32_e32 v13, v7, v13
	s_lshl_b64 s[0:1], s[4:5], 2
	s_add_u32 s0, s9, s0
	s_addc_u32 s1, s10, s1
	global_atomic_add_f32 v2, v13, s[0:1]
.Lrd1_nac:
	s_or_b64 exec, exec, s[6:7]
	s_waitcnt lgkmcnt(0)
.Lrd1_next:
	s_add_i32 s8, s8, s44
	s_cmpk_gt_i32 s8, 0x9ff
	s_cbranch_scc1 .LBB0_541
	s_branch .LBB0_536

.LBB0_669:
	v_readlane_b32 s4, v252, 42
	v_readlane_b32 s5, v252, 43
	v_readlane_b32 s3, v254, 5
	s_mov_b64 s[6:7], -1
	s_waitcnt lgkmcnt(0)
	s_nop 1
	global_load_dword v0, v2, s[4:5] sc1
	v_readlane_b32 s4, v252, 44
	v_readlane_b32 s5, v252, 45
	s_nop 4
	global_load_dword v1, v2, s[4:5] sc1
	v_readlane_b32 s4, v252, 46
	v_readlane_b32 s5, v252, 47
	s_nop 4
	global_load_dword v3, v2, s[4:5] sc1
	v_readlane_b32 s4, v252, 48
	v_readlane_b32 s5, v252, 49
	s_nop 4
	global_load_dword v4, v2, s[4:5] sc1
	v_readlane_b32 s4, v252, 50
	v_readlane_b32 s5, v252, 51
	s_nop 4
	global_load_dword v5, v2, s[4:5] sc1
	v_readlane_b32 s4, v252, 52
	v_readlane_b32 s5, v252, 53
	s_nop 4
	global_load_dword v6, v2, s[4:5] sc1
	v_readlane_b32 s4, v252, 54
	v_readlane_b32 s5, v252, 55
	s_nop 4
	global_load_dword v7, v2, s[4:5] sc1
	v_readlane_b32 s4, v252, 56
	v_readlane_b32 s5, v252, 57
	s_nop 4
	global_load_dword v8, v2, s[4:5] sc1
	v_readlane_b32 s4, v252, 58
	v_readlane_b32 s5, v252, 59
	s_nop 4
	global_load_dword v9, v2, s[4:5] sc1
	v_readlane_b32 s4, v252, 60
	v_readlane_b32 s5, v252, 61
	s_nop 4
	global_load_dword v10, v2, s[4:5] sc1
	v_readlane_b32 s4, v252, 62
	v_readlane_b32 s5, v252, 63
	s_nop 4
	global_load_dword v11, v2, s[4:5] sc1
	v_readlane_b32 s4, v253, 0
	v_readlane_b32 s5, v253, 1
	s_nop 4
	global_load_dword v12, v2, s[4:5] sc1
	v_readlane_b32 s4, v253, 2
	v_readlane_b32 s5, v253, 3
	s_nop 4
	global_load_dword v13, v2, s[4:5] sc1
	v_readlane_b32 s4, v253, 4
	v_readlane_b32 s5, v253, 5
	s_nop 4
	global_load_dword v14, v2, s[4:5] sc1
	v_readlane_b32 s4, v253, 6
	v_readlane_b32 s5, v253, 7
	s_nop 4
	global_load_dword v15, v2, s[4:5] sc1
	v_readlane_b32 s4, v253, 8
	v_readlane_b32 s5, v253, 9
	s_nop 4
	global_load_dword v16, v2, s[4:5] sc1
	s_mov_b64 s[4:5], -1
	s_waitcnt vmcnt(0)
	v_add_u32_e32 v17, v1, v0
	v_add_u32_e32 v17, v17, v3
	v_add_u32_e32 v17, v17, v4
	v_add_u32_e32 v17, v17, v5
	v_add_u32_e32 v17, v17, v6
	v_add_u32_e32 v17, v17, v7
	v_add_u32_e32 v17, v17, v8
	v_add_u32_e32 v17, v17, v9
	v_add_u32_e32 v17, v17, v10
	v_add_u32_e32 v17, v17, v11
	v_add_u32_e32 v17, v17, v12
	v_add_u32_e32 v17, v17, v13
	v_add_u32_e32 v17, v17, v14
	v_add_u32_e32 v17, v17, v15
	v_add_u32_e32 v17, v17, v16
	v_cmp_eq_u32_e32 vcc, s3, v17
	s_cbranch_vccnz .LBB0_668
	s_and_b32 s4, s10, 0xff
	s_cmp_eq_u32 s4, 0
	s_mov_b64 s[4:5], -1
	s_mov_b64 s[8:9], -1
	s_sleep 1
	s_cbranch_scc0 .LBB0_673
	v_readlane_b32 s4, v252, 40
	v_readlane_b32 s5, v252, 41
	s_nop 4
	global_load_dword v17, v2, s[4:5] sc1
	s_waitcnt vmcnt(0)
	v_cmp_eq_u32_e32 vcc, 0, v17
	s_cbranch_vccnz .LBB0_675
	s_mov_b64 s[8:9], 0
	s_mov_b64 s[4:5], -1
